# attention unit 1 fast path: next-tile address math and global loads in the QK MFMA gaps, next-tile LDS writes in the PV MFMA gaps, 6-deep LDS fragment ring
# speedup vs baseline: 1.0036x; 1.0036x over previous
.LBB0_1479:
	s_cmp_lt_u32 s51, s48
	s_cselect_b64 s[36:37], -1, 0
	s_cmp_ge_u32 s51, s48
	s_cbranch_scc1 .LBB0_1482
	s_cmp_gt_i32 s52, s49
	s_cbranch_scc0 .LaF1_fast
	v_lshl_add_u64 v[66:67], s[2:3], 0, v[176:177]
	v_add_co_u32_e32 v68, vcc, 0x16020000, v66
	s_nop 1
	v_addc_co_u32_e32 v69, vcc, 0, v67, vcc
	v_add_co_u32_e32 v66, vcc, 0x16030000, v66
	s_nop 1
	v_addc_co_u32_e32 v67, vcc, 0, v67, vcc
	global_load_dwordx4 v[98:101], v[68:69], off
	global_load_dwordx4 v[102:105], v[66:67], off
	v_lshl_add_u64 v[68:69], s[2:3], 0, v[178:179]
	v_add_co_u32_e32 v70, vcc, 0x1a000000, v68
	v_lshl_add_u64 v[66:67], s[2:3], 0, v[174:175]
	s_nop 0
	v_addc_co_u32_e32 v71, vcc, 0, v69, vcc
	global_load_dwordx4 v[106:109], v[66:67], off
	global_load_dwordx4 v[114:117], v[70:71], off offset:128
	v_add_co_u32_e32 v66, vcc, 0x1a400000, v68
	s_nop 1
	v_addc_co_u32_e32 v67, vcc, 0, v69, vcc
	global_load_dwordx4 v[146:149], v[66:67], off offset:128
	s_cmp_gt_i32 s52, s49
	s_cbranch_scc0 .LBB0_1483

.LaF1_fast:
	s_bitcmp1_b32 s51, 0
	s_cselect_b32 s53, 0, 0xac00
	s_setprio 1
	v_add_u32_e32 v253, s53, v171
	v_add_u32_e32 v252, s53, v181
	ds_read_b128 v[196:199], v253
	ds_read_b128 v[200:203], v253 offset:12800
	ds_read_b128 v[204:207], v253 offset:32
	ds_read_b128 v[208:211], v253 offset:12832
	ds_read_b128 v[212:215], v253 offset:64
	ds_read_b128 v[216:219], v253 offset:12864
	s_waitcnt lgkmcnt(5)
	v_mfma_f32_32x32x16_bf16 v[66:81], v[196:199], v[110:113], 0
	ds_read_b128 v[220:223], v253 offset:96
	v_lshl_add_u64 v[244:245], s[2:3], 0, v[176:177]
	s_waitcnt lgkmcnt(5)
	v_mfma_f32_32x32x16_bf16 v[82:97], v[200:203], v[110:113], 0
	ds_read_b128 v[224:227], v253 offset:12896
	v_add_co_u32_e32 v246, vcc, 0x16020000, v244
	s_waitcnt lgkmcnt(5)
	v_mfma_f32_32x32x16_bf16 v[66:81], v[204:207], v[118:121], v[66:81]
	ds_read_b128 v[228:231], v253 offset:128
	s_nop 1
	s_waitcnt lgkmcnt(5)
	v_mfma_f32_32x32x16_bf16 v[82:97], v[208:211], v[118:121], v[82:97]
	ds_read_b128 v[232:235], v253 offset:12928
	v_addc_co_u32_e32 v247, vcc, 0, v245, vcc
	s_waitcnt lgkmcnt(5)
	v_mfma_f32_32x32x16_bf16 v[66:81], v[212:215], v[122:125], v[66:81]
	ds_read_b128 v[236:239], v253 offset:160
	v_add_co_u32_e32 v244, vcc, 0x16030000, v244
	s_waitcnt lgkmcnt(5)
	v_mfma_f32_32x32x16_bf16 v[82:97], v[216:219], v[122:125], v[82:97]
	ds_read_b128 v[240:243], v253 offset:12960
	s_nop 1
	s_waitcnt lgkmcnt(5)
	v_mfma_f32_32x32x16_bf16 v[66:81], v[220:223], v[126:129], v[66:81]
	ds_read_b128 v[196:199], v253 offset:192
	v_addc_co_u32_e32 v245, vcc, 0, v245, vcc
	s_waitcnt lgkmcnt(5)
	v_mfma_f32_32x32x16_bf16 v[82:97], v[224:227], v[126:129], v[82:97]
	ds_read_b128 v[200:203], v253 offset:12992
	global_load_dwordx4 v[98:101], v[246:247], off
	s_waitcnt lgkmcnt(5)
	v_mfma_f32_32x32x16_bf16 v[66:81], v[228:231], v[130:133], v[66:81]
	ds_read_b128 v[204:207], v253 offset:224
	global_load_dwordx4 v[102:105], v[244:245], off
	s_waitcnt lgkmcnt(5)
	v_mfma_f32_32x32x16_bf16 v[82:97], v[232:235], v[130:133], v[82:97]
	ds_read_b128 v[208:211], v253 offset:13024
	v_lshl_add_u64 v[246:247], s[2:3], 0, v[178:179]
	s_waitcnt lgkmcnt(5)
	v_mfma_f32_32x32x16_bf16 v[66:81], v[236:239], v[134:137], v[66:81]
	ds_read_b128 v[212:215], v253 offset:256
	v_add_co_u32_e32 v248, vcc, 0x1a000000, v246
	s_waitcnt lgkmcnt(5)
	v_mfma_f32_32x32x16_bf16 v[82:97], v[240:243], v[134:137], v[82:97]
	ds_read_b128 v[216:219], v253 offset:13056
	v_lshl_add_u64 v[244:245], s[2:3], 0, v[174:175]
	s_waitcnt lgkmcnt(5)
	v_mfma_f32_32x32x16_bf16 v[66:81], v[196:199], v[138:141], v[66:81]
	ds_read_b128 v[220:223], v253 offset:288
	s_nop 0
	s_waitcnt lgkmcnt(5)
	v_mfma_f32_32x32x16_bf16 v[82:97], v[200:203], v[138:141], v[82:97]
	ds_read_b128 v[224:227], v253 offset:13088
	v_addc_co_u32_e32 v249, vcc, 0, v247, vcc
	s_waitcnt lgkmcnt(5)
	v_mfma_f32_32x32x16_bf16 v[66:81], v[204:207], v[142:145], v[66:81]
	ds_read_b128 v[228:231], v253 offset:320
	global_load_dwordx4 v[106:109], v[244:245], off
	s_waitcnt lgkmcnt(5)
	v_mfma_f32_32x32x16_bf16 v[82:97], v[208:211], v[142:145], v[82:97]
	ds_read_b128 v[232:235], v253 offset:13120
	global_load_dwordx4 v[114:117], v[248:249], off offset:128
	s_waitcnt lgkmcnt(5)
	v_mfma_f32_32x32x16_bf16 v[66:81], v[212:215], v[150:153], v[66:81]
	ds_read_b128 v[236:239], v253 offset:352
	v_add_co_u32_e32 v244, vcc, 0x1a400000, v246
	s_waitcnt lgkmcnt(5)
	v_mfma_f32_32x32x16_bf16 v[82:97], v[216:219], v[150:153], v[82:97]
	ds_read_b128 v[240:243], v253 offset:13152
	s_nop 1
	s_waitcnt lgkmcnt(5)
	v_mfma_f32_32x32x16_bf16 v[66:81], v[220:223], v[154:157], v[66:81]
	v_addc_co_u32_e32 v245, vcc, 0, v247, vcc
	s_waitcnt lgkmcnt(4)
	v_mfma_f32_32x32x16_bf16 v[82:97], v[224:227], v[154:157], v[82:97]
	global_load_dwordx4 v[146:149], v[244:245], off offset:128
	s_waitcnt lgkmcnt(3)
	v_mfma_f32_32x32x16_bf16 v[66:81], v[228:231], v[158:161], v[66:81]
	s_waitcnt lgkmcnt(2)
	v_mfma_f32_32x32x16_bf16 v[82:97], v[232:235], v[158:161], v[82:97]
	s_waitcnt lgkmcnt(1)
	v_mfma_f32_32x32x16_bf16 v[66:81], v[236:239], v[162:165], v[66:81]
	s_waitcnt lgkmcnt(0)
	v_mfma_f32_32x32x16_bf16 v[82:97], v[240:243], v[162:165], v[82:97]
	ds_read_b128 v[196:199], v252 offset:25600
	ds_read_b128 v[200:203], v252 offset:25632
	ds_read_b128 v[204:207], v252 offset:25664
	ds_read_b128 v[208:211], v252 offset:25696
	ds_read_b128 v[212:215], v252 offset:30208
	ds_read_b128 v[216:219], v252 offset:30240
	s_setprio 0
	s_add_i32 s54, s52, 63
	s_cmp_le_i32 s54, s47
	s_cbranch_scc1 .LaF1_1
	v_add_u32_e32 v0, s52, v168
	v_add_u32_e32 v184, 32, v0
	v_cmp_le_i32_e32 vcc, v184, v173
	v_add_u32_e32 v184, 33, v0
	s_nop 3
	v_cndmask_b32_e32 v82, v180, v82, vcc
	v_cmp_lt_i32_e32 vcc, v0, v173
	s_nop 1
	v_cndmask_b32_e32 v67, v180, v67, vcc
	v_cmp_le_i32_e32 vcc, v0, v173
	s_nop 1
	v_cndmask_b32_e32 v66, v180, v66, vcc
	v_cmp_le_i32_e32 vcc, v184, v173
	v_add_u32_e32 v184, 2, v0
	s_nop 0
	v_cndmask_b32_e32 v83, v180, v83, vcc
	v_cmp_le_i32_e32 vcc, v184, v173
	v_add_u32_e32 v184, 34, v0
	s_nop 0
	v_cndmask_b32_e32 v68, v180, v68, vcc
	v_cmp_le_i32_e32 vcc, v184, v173
	v_add_u32_e32 v184, 3, v0
	s_nop 0
	v_cndmask_b32_e32 v84, v180, v84, vcc
	v_cmp_le_i32_e32 vcc, v184, v173
	v_add_u32_e32 v184, 35, v0
	s_nop 0
	v_cndmask_b32_e32 v69, v180, v69, vcc
	v_cmp_le_i32_e32 vcc, v184, v173
	v_add_u32_e32 v184, 4, v0
	s_nop 0
	v_cndmask_b32_e32 v85, v180, v85, vcc
	v_cmp_le_i32_e32 vcc, v184, v173
	v_add_u32_e32 v184, 36, v0
	s_nop 0
	v_cndmask_b32_e32 v70, v180, v70, vcc
	v_cmp_le_i32_e32 vcc, v184, v173
	v_add_u32_e32 v184, 5, v0
	s_nop 0
	v_cndmask_b32_e32 v86, v180, v86, vcc
	v_cmp_le_i32_e32 vcc, v184, v173
	v_add_u32_e32 v184, 37, v0
	s_nop 0
	v_cndmask_b32_e32 v71, v180, v71, vcc
	v_cmp_le_i32_e32 vcc, v184, v173
	v_add_u32_e32 v184, 6, v0
	s_nop 0
	v_cndmask_b32_e32 v87, v180, v87, vcc
	v_cmp_le_i32_e32 vcc, v184, v173
	v_add_u32_e32 v184, 38, v0
	s_nop 0
	v_cndmask_b32_e32 v72, v180, v72, vcc
	v_cmp_le_i32_e32 vcc, v184, v173
	v_add_u32_e32 v184, 7, v0
	s_nop 0
	v_cndmask_b32_e32 v88, v180, v88, vcc
	v_cmp_le_i32_e32 vcc, v184, v173
	v_add_u32_e32 v184, 39, v0
	s_nop 0
	v_cndmask_b32_e32 v73, v180, v73, vcc
	v_cmp_le_i32_e32 vcc, v184, v173
	v_add_u32_e32 v184, 16, v0
	s_nop 0
	v_cndmask_b32_e32 v89, v180, v89, vcc
	v_cmp_le_i32_e32 vcc, v184, v173
	v_add_u32_e32 v184, 48, v0
	s_nop 0
	v_cndmask_b32_e32 v74, v180, v74, vcc
	v_cmp_le_i32_e32 vcc, v184, v173
	v_add_u32_e32 v184, 17, v0
	s_nop 0
	v_cndmask_b32_e32 v90, v180, v90, vcc
	v_cmp_le_i32_e32 vcc, v184, v173
	v_add_u32_e32 v184, 49, v0
	s_nop 0
	v_cndmask_b32_e32 v75, v180, v75, vcc
	v_cmp_le_i32_e32 vcc, v184, v173
	v_add_u32_e32 v184, 18, v0
	s_nop 0
	v_cndmask_b32_e32 v91, v180, v91, vcc
	v_cmp_le_i32_e32 vcc, v184, v173
	v_add_u32_e32 v184, 50, v0
	s_nop 0
	v_cndmask_b32_e32 v76, v180, v76, vcc
	v_cmp_le_i32_e32 vcc, v184, v173
	v_add_u32_e32 v184, 19, v0
	s_nop 0
	v_cndmask_b32_e32 v92, v180, v92, vcc
	v_cmp_le_i32_e32 vcc, v184, v173
	v_add_u32_e32 v184, 51, v0
	s_nop 0
	v_cndmask_b32_e32 v77, v180, v77, vcc
	v_cmp_le_i32_e32 vcc, v184, v173
	v_add_u32_e32 v184, 20, v0
	s_nop 0
	v_cndmask_b32_e32 v93, v180, v93, vcc
	v_cmp_le_i32_e32 vcc, v184, v173
	v_add_u32_e32 v184, 52, v0
	s_nop 0
	v_cndmask_b32_e32 v78, v180, v78, vcc
	v_cmp_le_i32_e32 vcc, v184, v173
	v_add_u32_e32 v184, 21, v0
	s_nop 0
	v_cndmask_b32_e32 v94, v180, v94, vcc
	v_cmp_le_i32_e32 vcc, v184, v173
	v_add_u32_e32 v184, 53, v0
	s_nop 0
	v_cndmask_b32_e32 v79, v180, v79, vcc
	v_cmp_le_i32_e32 vcc, v184, v173
	v_add_u32_e32 v184, 22, v0
	s_nop 0
	v_cndmask_b32_e32 v95, v180, v95, vcc
	v_cmp_le_i32_e32 vcc, v184, v173
	v_add_u32_e32 v184, 54, v0
	s_nop 0
	v_cndmask_b32_e32 v80, v180, v80, vcc
	v_cmp_le_i32_e32 vcc, v184, v173
	v_add_u32_e32 v184, 23, v0
	v_add_u32_e32 v0, 55, v0
	v_cndmask_b32_e32 v96, v180, v96, vcc
	v_cmp_le_i32_e32 vcc, v184, v173
	s_nop 1
	v_cndmask_b32_e32 v81, v180, v81, vcc
	v_cmp_le_i32_e32 vcc, v0, v173
	s_nop 1
	v_cndmask_b32_e32 v97, v180, v97, vcc

.LaF1_2:
	v_sub_f32_e32 v0, v66, v183
	v_exp_f32_e32 v184, v0
	v_sub_f32_e32 v0, v82, v183
	v_exp_f32_e32 v185, v0
	v_sub_f32_e32 v0, v67, v183
	v_exp_f32_e32 v66, v0
	v_sub_f32_e32 v0, v83, v183
	v_exp_f32_e32 v0, v0
	v_add_f32_e32 v67, v184, v185
	v_pk_add_f32 v[82:83], v[66:67], v[0:1]
	v_sub_f32_e32 v67, v68, v183
	v_sub_f32_e32 v68, v84, v183
	v_pk_add_f32 v[82:83], v[82:83], v[82:83] op_sel_hi:[0,1]
	v_exp_f32_e32 v67, v67
	v_exp_f32_e32 v186, v68
	v_sub_f32_e32 v68, v69, v183
	v_sub_f32_e32 v69, v85, v183
	v_exp_f32_e32 v68, v68
	v_exp_f32_e32 v82, v69
	v_add_f32_e32 v69, v67, v186
	v_cvt_pk_bf16_f32 v66, v184, v66
	v_cvt_pk_bf16_f32 v67, v67, v68
	v_pk_add_f32 v[84:85], v[68:69], v[82:83]
	v_sub_f32_e32 v69, v70, v183
	v_sub_f32_e32 v70, v86, v183
	v_pk_add_f32 v[84:85], v[84:85], v[84:85] op_sel_hi:[0,1]
	v_exp_f32_e32 v69, v69
	v_exp_f32_e32 v83, v70
	v_sub_f32_e32 v70, v71, v183
	v_sub_f32_e32 v71, v87, v183
	v_exp_f32_e32 v70, v70
	v_exp_f32_e32 v84, v71
	v_add_f32_e32 v71, v69, v83
	v_cvt_pk_bf16_f32 v68, v69, v70
	v_pk_add_f32 v[86:87], v[70:71], v[84:85]
	v_sub_f32_e32 v71, v72, v183
	v_sub_f32_e32 v72, v88, v183
	v_pk_add_f32 v[86:87], v[86:87], v[86:87] op_sel_hi:[0,1]
	v_exp_f32_e32 v71, v71
	v_exp_f32_e32 v85, v72
	v_sub_f32_e32 v72, v73, v183
	v_sub_f32_e32 v73, v89, v183
	v_exp_f32_e32 v72, v72
	v_exp_f32_e32 v86, v73
	v_add_f32_e32 v73, v71, v85
	v_cvt_pk_bf16_f32 v69, v71, v72
	v_pk_add_f32 v[88:89], v[72:73], v[86:87]
	v_sub_f32_e32 v73, v74, v183
	v_sub_f32_e32 v74, v90, v183
	v_pk_add_f32 v[88:89], v[88:89], v[88:89] op_sel_hi:[0,1]
	v_exp_f32_e32 v73, v73
	v_exp_f32_e32 v87, v74
	v_sub_f32_e32 v74, v75, v183
	v_sub_f32_e32 v75, v91, v183
	v_exp_f32_e32 v74, v74
	v_exp_f32_e32 v88, v75
	v_add_f32_e32 v75, v73, v87
	v_cvt_pk_bf16_f32 v70, v73, v74
	v_pk_add_f32 v[90:91], v[74:75], v[88:89]
	v_sub_f32_e32 v75, v76, v183
	v_sub_f32_e32 v76, v92, v183
	v_pk_add_f32 v[90:91], v[90:91], v[90:91] op_sel_hi:[0,1]
	v_exp_f32_e32 v75, v75
	v_exp_f32_e32 v89, v76
	v_sub_f32_e32 v76, v77, v183
	v_sub_f32_e32 v77, v93, v183
	v_exp_f32_e32 v76, v76
	v_exp_f32_e32 v90, v77
	v_add_f32_e32 v77, v75, v89
	v_cvt_pk_bf16_f32 v71, v75, v76
	v_pk_add_f32 v[92:93], v[76:77], v[90:91]
	v_sub_f32_e32 v77, v78, v183
	v_sub_f32_e32 v78, v94, v183
	v_pk_add_f32 v[92:93], v[92:93], v[92:93] op_sel_hi:[0,1]
	v_exp_f32_e32 v77, v77
	v_exp_f32_e32 v91, v78
	v_sub_f32_e32 v78, v79, v183
	v_sub_f32_e32 v79, v95, v183
	v_exp_f32_e32 v78, v78
	v_exp_f32_e32 v92, v79
	v_add_f32_e32 v79, v77, v91
	v_cvt_pk_bf16_f32 v72, v77, v78
	v_pk_add_f32 v[94:95], v[78:79], v[92:93]
	v_sub_f32_e32 v79, v80, v183
	v_sub_f32_e32 v80, v96, v183
	v_pk_add_f32 v[94:95], v[94:95], v[94:95] op_sel_hi:[0,1]
	v_exp_f32_e32 v79, v79
	v_exp_f32_e32 v93, v80
	v_sub_f32_e32 v80, v81, v183
	v_sub_f32_e32 v81, v97, v183
	v_exp_f32_e32 v80, v80
	v_exp_f32_e32 v94, v81
	v_add_f32_e32 v81, v79, v93
	v_cvt_pk_bf16_f32 v73, v79, v80
	v_cvt_pk_bf16_f32 v74, v185, v0
	v_pk_add_f32 v[96:97], v[80:81], v[94:95]
	v_cvt_pk_bf16_f32 v75, v186, v82
	v_cvt_pk_bf16_f32 v76, v83, v84
	v_cvt_pk_bf16_f32 v77, v85, v86
	v_cvt_pk_bf16_f32 v78, v87, v88
	v_cvt_pk_bf16_f32 v79, v89, v90
	s_nop 0
	v_add_f32_e32 v95, v96, v97
	v_cvt_pk_bf16_f32 v80, v91, v92
	v_cvt_pk_bf16_f32 v81, v93, v94
	s_setprio 1
	v_add_f32_e32 v182, v182, v95
	s_waitcnt lgkmcnt(5)
	v_mfma_f32_32x32x16_bf16 v[50:65], v[196:199], v[66:69], v[50:65]
	ds_read_b128 v[220:223], v252 offset:30272
	s_bitcmp1_b32 s51, 0
	s_waitcnt lgkmcnt(5)
	v_mfma_f32_32x32x16_bf16 v[50:65], v[200:203], v[70:73], v[50:65]
	ds_read_b128 v[224:227], v252 offset:30304
	s_cselect_b32 s99, 0xac00, 0
	s_waitcnt lgkmcnt(5)
	v_mfma_f32_32x32x16_bf16 v[50:65], v[204:207], v[74:77], v[50:65]
	ds_read_b128 v[228:231], v252 offset:34816
	s_add_i32 s99, s99, 0
	s_waitcnt lgkmcnt(5)
	v_mfma_f32_32x32x16_bf16 v[50:65], v[208:211], v[78:81], v[50:65]
	ds_read_b128 v[232:235], v252 offset:34848
	v_add_u32_e32 v250, s99, v170
	s_waitcnt lgkmcnt(5)
	v_mfma_f32_32x32x16_bf16 v[34:49], v[212:215], v[66:69], v[34:49]
	ds_read_b128 v[236:239], v252 offset:34880
	s_waitcnt vmcnt(4)
	s_waitcnt lgkmcnt(5)
	v_mfma_f32_32x32x16_bf16 v[34:49], v[216:219], v[70:73], v[34:49]
	ds_read_b128 v[240:243], v252 offset:34912
	ds_write_b128 v250, v[98:101]
	s_waitcnt lgkmcnt(6)
	v_mfma_f32_32x32x16_bf16 v[34:49], v[220:223], v[74:77], v[34:49]
	ds_read_b128 v[196:199], v252 offset:39424
	s_waitcnt vmcnt(3)
	s_waitcnt lgkmcnt(6)
	v_mfma_f32_32x32x16_bf16 v[34:49], v[224:227], v[78:81], v[34:49]
	ds_read_b128 v[200:203], v252 offset:39456
	ds_write_b128 v250, v[102:105] offset:12800
	s_waitcnt lgkmcnt(7)
	v_mfma_f32_32x32x16_bf16 v[18:33], v[228:231], v[66:69], v[18:33]
	ds_read_b128 v[204:207], v252 offset:39488
	v_add_u32_e32 v250, s99, v172
	s_waitcnt lgkmcnt(7)
	v_mfma_f32_32x32x16_bf16 v[18:33], v[232:235], v[70:73], v[18:33]
	ds_read_b128 v[208:211], v252 offset:39520
	s_waitcnt vmcnt(2)
	s_waitcnt lgkmcnt(7)
	v_mfma_f32_32x32x16_bf16 v[18:33], v[236:239], v[74:77], v[18:33]
	ds_write_b128 v250, v[106:109] offset:256
	s_waitcnt lgkmcnt(7)
	v_mfma_f32_32x32x16_bf16 v[18:33], v[240:243], v[78:81], v[18:33]
	v_add_u32_e32 v250, s99, v169
	s_waitcnt lgkmcnt(5)
	v_mfma_f32_32x32x16_bf16 v[2:17], v[196:199], v[66:69], v[2:17]
	s_waitcnt vmcnt(1)
	s_waitcnt lgkmcnt(4)
	v_mfma_f32_32x32x16_bf16 v[2:17], v[200:203], v[70:73], v[2:17]
	ds_write_b128 v250, v[114:117] offset:25600
	s_waitcnt lgkmcnt(3)
	v_mfma_f32_32x32x16_bf16 v[2:17], v[204:207], v[74:77], v[2:17]
	s_waitcnt vmcnt(0)
	s_waitcnt lgkmcnt(2)
	v_mfma_f32_32x32x16_bf16 v[2:17], v[208:211], v[78:81], v[2:17]
	ds_write_b128 v250, v[146:149] offset:34816
	s_setprio 0
	s_branch .LBB0_1478

	.amdhsa_kernel _Z8fwd_mega4Args
		.amdhsa_group_segment_fixed_size 0
		.amdhsa_private_segment_fixed_size 0
		.amdhsa_kernarg_size 552
		.amdhsa_user_sgpr_count 2
		.amdhsa_user_sgpr_dispatch_ptr 0
		.amdhsa_user_sgpr_queue_ptr 0
		.amdhsa_user_sgpr_kernarg_segment_ptr 1
		.amdhsa_user_sgpr_dispatch_id 0
		.amdhsa_user_sgpr_kernarg_preload_length 0
		.amdhsa_user_sgpr_kernarg_preload_offset 0
		.amdhsa_user_sgpr_private_segment_size 0
		.amdhsa_uses_dynamic_stack 0
		.amdhsa_enable_private_segment 0
		.amdhsa_system_sgpr_workgroup_id_x 1
		.amdhsa_system_sgpr_workgroup_id_y 0
		.amdhsa_system_sgpr_workgroup_id_z 0
		.amdhsa_system_sgpr_workgroup_info 0
		.amdhsa_system_vgpr_workitem_id 2
		.amdhsa_next_free_vgpr 255
		.amdhsa_next_free_sgpr 102
		.amdhsa_accum_offset 256
		.amdhsa_reserve_vcc 1
		.amdhsa_float_round_mode_32 0
		.amdhsa_float_round_mode_16_64 0
		.amdhsa_float_denorm_mode_32 3
		.amdhsa_float_denorm_mode_16_64 3
		.amdhsa_dx10_clamp 1
		.amdhsa_ieee_mode 1
		.amdhsa_fp16_overflow 0
		.amdhsa_tg_split 0
		.amdhsa_exception_fp_ieee_invalid_op 0
		.amdhsa_exception_fp_denorm_src 0
		.amdhsa_exception_fp_ieee_div_zero 0
		.amdhsa_exception_fp_ieee_overflow 0
		.amdhsa_exception_fp_ieee_underflow 0
		.amdhsa_exception_fp_ieee_inexact 0
		.amdhsa_exception_int_div_zero 0
	.end_amdhsa_kernel

amdhsa.kernels:
  - .agpr_count:     0
    .args:
      - .offset:         0
        .size:           296
        .value_kind:     by_value
      - .offset:         296
        .size:           4
        .value_kind:     hidden_block_count_x
      - .offset:         300
        .size:           4
        .value_kind:     hidden_block_count_y
      - .offset:         304
        .size:           4
        .value_kind:     hidden_block_count_z
      - .offset:         308
        .size:           2
        .value_kind:     hidden_group_size_x
      - .offset:         310
        .size:           2
        .value_kind:     hidden_group_size_y
      - .offset:         312
        .size:           2
        .value_kind:     hidden_group_size_z
      - .offset:         314
        .size:           2
        .value_kind:     hidden_remainder_x
      - .offset:         316
        .size:           2
        .value_kind:     hidden_remainder_y
      - .offset:         318
        .size:           2
        .value_kind:     hidden_remainder_z
      - .offset:         336
        .size:           8
        .value_kind:     hidden_global_offset_x
      - .offset:         344
        .size:           8
        .value_kind:     hidden_global_offset_y
      - .offset:         352
        .size:           8
        .value_kind:     hidden_global_offset_z
      - .offset:         360
        .size:           2
        .value_kind:     hidden_grid_dims
      - .offset:         384
        .size:           8
        .value_kind:     hidden_multigrid_sync_arg
      - .offset:         416
        .size:           4
        .value_kind:     hidden_dynamic_lds_size
    .group_segment_fixed_size: 0
    .kernarg_segment_align: 8
    .kernarg_segment_size: 552
    .language:       OpenCL C
    .language_version:
      - 2
      - 0
    .max_flat_workgroup_size: 512
    .name:           _Z8fwd_mega4Args
    .private_segment_fixed_size: 0
    .sgpr_count:     108
    .sgpr_spill_count: 4
    .symbol:         _Z8fwd_mega4Args.kd
    .uniform_work_group_size: 1
    .uses_dynamic_stack: false
    .vgpr_count:     255
    .vgpr_spill_count: 0
    .wavefront_size: 64
